# GU epilogue: 160 packed v_pk_mul/add_f32 replaced by scalar f32 pairs (instruction selection, bitwise-identical math)
# baseline (speedup 1.0000x reference)
; __device__ __forceinline__ float ssq_rs(ssq_t v) { return __builtin_amdgcn_rsqf((float)v * (1.0f / (16777216.0f * 1024.0f)) + RMS_EPS); }
;     __device__ __forceinline__ void operator()(const f32x4 (&acc)[2][2][4][2], const Unit& u, int wr, int wc, int fr, int fq) const {
;         const int row0 = u.pm * BM + wr * 64 + fr, col0 = u.pn * HALF + wc * 32 + 8 * fq;
;         float rsv[2][4]; ssq_t sv[2][4];
; #pragma unroll
;         for (int ai = 0; ai < 2; ++ai)
; #pragma unroll
;             for (int m = 0; m < 4; ++m) sv[ai][m] = ssq[row0 + ai * HALF + m * 16];
; #pragma unroll
;         for (int ai = 0; ai < 2; ++ai)
; #pragma unroll
;             for (int m = 0; m < 4; ++m) rsv[ai][m] = ssq_rs(sv[ai][m]);
;         asm volatile("" ::: "memory");
; #pragma unroll
;         for (int ai = 0; ai < 2; ++ai)
; #pragma unroll
;             for (int m = 0; m < 4; ++m) {
;                 const int row = row0 + ai * HALF + m * 16;
;                 const float rs = rsv[ai][m], nrs = rs * -1.44269504089f, rs2 = rs * rs;
;                 typedef float f32x2 __attribute__((ext_vector_type(2)));
;                 float a[8];
; #pragma unroll
;                 for (int n = 0; n < 2; ++n)
; #pragma unroll
;                     for (int hf = 0; hf < 2; ++hf) {
;                         const f32x2 g2 = (f32x2){acc[ai][0][m][n][2 * hf], acc[ai][0][m][n][2 * hf + 1]}, u2 = (f32x2){acc[ai][1][m][n][2 * hf], acc[ai][1][m][n][2 * hf + 1]};
;                         const f32x2 t = g2 * nrs;
;                         f32x2 e; e.x = __builtin_amdgcn_exp2f(t.x); e.y = __builtin_amdgcn_exp2f(t.y);
;                         const f32x2 d = e + 1.0f;
;                         f32x2 r; r.x = __builtin_amdgcn_rcpf(d.x); r.y = __builtin_amdgcn_rcpf(d.y);
;                         const f32x2 o = (g2 * u2) * (r * rs2);
.LBB0_131:
	v_add_u32_e32 v141, 0x14000, v147
	ds_read_b128 v[168:171], v141
	ds_read_b128 v[172:175], v141 offset:1024
	ds_read_b128 v[176:179], v141 offset:2048
	ds_read_b128 v[180:183], v141 offset:3072
	ds_read_b128 v[184:187], v150
	ds_read_b128 v[188:191], v150 offset:1024
	ds_read_b128 v[200:203], v150 offset:2048
	ds_read_b128 v[204:207], v150 offset:3072
	ds_read_b128 v[208:211], v150 offset:4096
	ds_read_b128 v[212:215], v150 offset:5120
	ds_read_b128 v[216:219], v150 offset:6144
	ds_read_b128 v[220:223], v150 offset:7168
	v_mul_f32_e32 v126, v122, v126
	v_mul_f32_e32 v127, v123, v127
	v_mul_f32_e32 v118, v114, v118
	v_mul_f32_e32 v119, v115, v119
	s_lshl_b32 s6, s16, 7
	s_or_b32 s6, s6, s35
	s_ashr_i32 s6, s6, 6
	s_mul_i32 s7, s58, 44
	s_add_i32 s6, s6, s7
	s_ashr_i32 s7, s6, 31
	s_lshl_b64 s[6:7], s[6:7], 15
	s_add_u32 s46, s62, s6
	s_addc_u32 s47, s63, s7
	v_mul_f32_e32 v104, v108, v104
	v_mul_f32_e32 v105, v109, v105
	v_mul_f32_e32 v106, v110, v106
	v_mul_f32_e32 v107, v111, v107
	v_mul_f32_e32 v102, v98, v102
	v_mul_f32_e32 v103, v99, v103
	v_mul_f32_e32 v88, v92, v88
	v_mul_f32_e32 v89, v93, v89
	v_mul_f32_e32 v90, v94, v90
	v_mul_f32_e32 v91, v95, v91
	v_mul_f32_e32 v86, v82, v86
	v_mul_f32_e32 v87, v83, v87
	v_mul_f32_e32 v72, v76, v72
	v_mul_f32_e32 v73, v77, v73
	v_mul_f32_e32 v74, v78, v74
	v_mul_f32_e32 v75, v79, v75
	v_mul_f32_e32 v70, v66, v70
	v_mul_f32_e32 v71, v67, v71
	v_mul_f32_e32 v56, v60, v56
	v_mul_f32_e32 v57, v61, v57
	v_mul_f32_e32 v58, v62, v58
	v_mul_f32_e32 v59, v63, v59
	v_mul_f32_e32 v54, v50, v54
	v_mul_f32_e32 v55, v51, v55
	v_mul_f32_e32 v40, v44, v40
	v_mul_f32_e32 v41, v45, v41
	v_mul_f32_e32 v42, v46, v42
	v_mul_f32_e32 v43, v47, v43
	v_mul_f32_e32 v38, v34, v38
	v_mul_f32_e32 v39, v35, v39
	v_mul_f32_e32 v24, v28, v24
	v_mul_f32_e32 v25, v29, v25
	v_mul_f32_e32 v26, v30, v26
	v_mul_f32_e32 v27, v31, v27
	v_mul_f32_e32 v22, v18, v22
	v_mul_f32_e32 v23, v19, v23
	v_mul_f32_e32 v8, v12, v8
	v_mul_f32_e32 v9, v13, v9
	v_mul_f32_e32 v10, v14, v10
	v_mul_f32_e32 v11, v15, v11
	v_mul_f32_e32 v0, v4, v0
	v_mul_f32_e32 v1, v5, v1
	v_mul_f32_e32 v2, v6, v2
	v_mul_f32_e32 v3, v7, v3
	s_waitcnt vmcnt(6)
	v_mov_b32_e32 v152, v238
	v_mov_b32_e32 v153, v239
	v_mov_b32_e32 v154, v240
	v_mov_b32_e32 v155, v241
	v_mov_b32_e32 v158, v242
	v_mov_b32_e32 v159, v243
	v_mov_b32_e32 v160, v244
	v_mov_b32_e32 v161, v245
	v_mov_b32_e32 v162, v246
	v_mov_b32_e32 v163, v247
	v_mov_b32_e32 v164, v248
	v_mov_b32_e32 v165, v249
	v_mov_b32_e32 v166, v250
	v_mov_b32_e32 v167, v251
	v_mov_b32_e32 v148, v228
	v_mov_b32_e32 v149, v229
	v_ffbh_u32_e32 v141, v153
	v_min_u32_e32 v141, 32, v141
	v_lshlrev_b64 v[152:153], v141, v[152:153]
	v_min_u32_e32 v143, 1, v152
	v_or_b32_e32 v143, v153, v143
	v_cvt_f32_u32_e32 v143, v143
	v_sub_u32_e32 v141, 32, v141
	v_ldexp_f32 v141, v143, v141
	v_ffbh_u32_e32 v143, v155
	v_min_u32_e32 v143, 32, v143
	v_lshlrev_b64 v[152:153], v143, v[154:155]
	v_min_u32_e32 v144, 1, v152
	v_or_b32_e32 v144, v153, v144
	v_cvt_f32_u32_e32 v144, v144
	v_sub_u32_e32 v143, 32, v143
	v_fmamk_f32 v141, v141, 0x2e800000, v193
	v_rsq_f32_e32 v141, v141
	v_ldexp_f32 v143, v144, v143
	v_fmamk_f32 v143, v143, 0x2e800000, v193
	v_rsq_f32_e32 v156, v143
	v_ffbh_u32_e32 v143, v159
	v_min_u32_e32 v143, 32, v143
	v_lshlrev_b64 v[152:153], v143, v[158:159]
	v_min_u32_e32 v144, 1, v152
	v_or_b32_e32 v144, v153, v144
	v_cvt_f32_u32_e32 v144, v144
	v_sub_u32_e32 v143, 32, v143
	v_ldexp_f32 v143, v144, v143
	v_fmamk_f32 v143, v143, 0x2e800000, v193
	v_rsq_f32_e32 v155, v143
	v_ffbh_u32_e32 v143, v161
	v_min_u32_e32 v143, 32, v143
	v_lshlrev_b64 v[152:153], v143, v[160:161]
	v_min_u32_e32 v144, 1, v152
	v_or_b32_e32 v144, v153, v144
	v_cvt_f32_u32_e32 v144, v144
	v_sub_u32_e32 v143, 32, v143
	v_ldexp_f32 v143, v144, v143
	v_fmamk_f32 v143, v143, 0x2e800000, v193
	v_rsq_f32_e32 v154, v143
	v_ffbh_u32_e32 v143, v163
	v_min_u32_e32 v143, 32, v143
	v_lshlrev_b64 v[152:153], v143, v[162:163]
	v_min_u32_e32 v144, 1, v152
	v_or_b32_e32 v144, v153, v144
	v_cvt_f32_u32_e32 v144, v144
	v_sub_u32_e32 v143, 32, v143
	v_ldexp_f32 v143, v144, v143
	v_ffbh_u32_e32 v144, v165
	v_min_u32_e32 v144, 32, v144
	v_lshlrev_b64 v[152:153], v144, v[164:165]
	v_min_u32_e32 v146, 1, v152
	v_or_b32_e32 v146, v153, v146
	v_cvt_f32_u32_e32 v146, v146
	v_sub_u32_e32 v144, 32, v144
	v_fmamk_f32 v143, v143, 0x2e800000, v193
	v_rsq_f32_e32 v143, v143
	v_ldexp_f32 v144, v146, v144
	v_fmamk_f32 v144, v144, 0x2e800000, v193
	v_rsq_f32_e32 v153, v144
	v_ffbh_u32_e32 v144, v167
	v_min_u32_e32 v144, 32, v144
	v_lshlrev_b64 v[158:159], v144, v[166:167]
	v_min_u32_e32 v146, 1, v158
	v_or_b32_e32 v146, v159, v146
	v_cvt_f32_u32_e32 v146, v146
	v_sub_u32_e32 v144, 32, v144
	v_ldexp_f32 v144, v146, v144
	v_fmamk_f32 v144, v144, 0x2e800000, v193
	v_rsq_f32_e32 v152, v144
	v_ffbh_u32_e32 v144, v149
	v_min_u32_e32 v144, 32, v144
	v_lshlrev_b64 v[148:149], v144, v[148:149]
	v_min_u32_e32 v146, 1, v148
	v_or_b32_e32 v146, v149, v146
	v_cvt_f32_u32_e32 v146, v146
	v_sub_u32_e32 v144, 32, v144
	v_ldexp_f32 v144, v146, v144
	v_mul_f32_e32 v146, 0xbfb8aa3b, v141
	v_mul_f32_e32 v148, v120, v146
	v_mul_f32_e32 v149, v121, v146
	v_fmamk_f32 v144, v144, 0x2e800000, v193
	v_exp_f32_e32 v148, v148
	v_exp_f32_e32 v149, v149
	v_rsq_f32_e32 v151, v144
	v_mul_f32_e32 v144, v141, v141
	v_mul_f32_e32 v120, v120, v124
	v_mul_f32_e32 v121, v121, v125
	v_add_f32_e32 v148, 1.0, v148
	v_add_f32_e32 v149, 1.0, v149
	v_mul_f32_e32 v122, v122, v146
	v_mul_f32_e32 v123, v123, v146
	v_rcp_f32_e32 v148, v148
	v_rcp_f32_e32 v149, v149
	v_mul_f32_e32 v114, v114, v146
	v_mul_f32_e32 v115, v115, v146
; __device__ __forceinline__ unsigned cvt_pk_bf16(float lo, float hi) { unsigned r; asm volatile("v_cvt_pk_bf16_f32 %0, %1, %2" : "=v"(r) : "v"(lo), "v"(hi)); return r; }
;     __device__ __forceinline__ void operator()(const f32x4 (&acc)[2][2][4][2], const Unit& u, int wr, int wc, int fr, int fq) const {
;     ...
;             for (int m = 0; m < 4; ++m) {
;                 const int row = row0 + ai * HALF + m * 16;
;                 const float rs = rsv[ai][m], nrs = rs * -1.44269504089f, rs2 = rs * rs;
;                 typedef float f32x2 __attribute__((ext_vector_type(2)));
;                 float a[8];
; #pragma unroll
;                 for (int n = 0; n < 2; ++n)
; #pragma unroll
;                     for (int hf = 0; hf < 2; ++hf) {
;                         const f32x2 g2 = (f32x2){acc[ai][0][m][n][2 * hf], acc[ai][0][m][n][2 * hf + 1]}, u2 = (f32x2){acc[ai][1][m][n][2 * hf], acc[ai][1][m][n][2 * hf + 1]};
;                         const f32x2 t = g2 * nrs;
;                         f32x2 e; e.x = __builtin_amdgcn_exp2f(t.x); e.y = __builtin_amdgcn_exp2f(t.y);
;                         const f32x2 d = e + 1.0f;
;                         f32x2 r; r.x = __builtin_amdgcn_rcpf(d.x); r.y = __builtin_amdgcn_rcpf(d.y);
;                         const f32x2 o = (g2 * u2) * (r * rs2);
;                         a[n * 4 + 2 * hf] = o.x; a[n * 4 + 2 * hf + 1] = o.y;
;                     }
;                 u32x4 w; w.x = cvt_pk_bf16(a[0], a[1]); w.y = cvt_pk_bf16(a[2], a[3]); w.z = cvt_pk_bf16(a[4], a[5]); w.w = cvt_pk_bf16(a[6], a[7]);
;                 __builtin_nontemporal_store(w, (u32x4*)(O + ((size_t)(u.pm * (ldc >> 6) + (col0 >> 6)) * 256 + (row & 255)) * 64 + (col0 & 63)));
	v_exp_f32_e32 v122, v122
	v_exp_f32_e32 v123, v123
	v_mul_f32_e32 v124, v144, v148
	v_mul_f32_e32 v125, v144, v149
	v_mul_f32_e32 v120, v120, v124
	v_mul_f32_e32 v121, v121, v125
	v_mul_f32_e32 v124, v112, v146
	v_mul_f32_e32 v125, v113, v146
	v_exp_f32_e32 v114, v114
	v_exp_f32_e32 v124, v124
	v_exp_f32_e32 v125, v125
	v_exp_f32_e32 v115, v115
	v_add_f32_e32 v122, 1.0, v122
	v_add_f32_e32 v123, 1.0, v123
	v_mul_f32_e32 v112, v112, v116
	v_mul_f32_e32 v113, v113, v117
	v_add_f32_e32 v124, 1.0, v124
	v_add_f32_e32 v125, 1.0, v125
	v_add_f32_e32 v114, 1.0, v114
	v_add_f32_e32 v115, 1.0, v115
	v_rcp_f32_e32 v124, v124
	v_rcp_f32_e32 v125, v125
	v_rcp_f32_e32 v122, v122
	v_rcp_f32_e32 v123, v123
	v_rcp_f32_e32 v114, v114
	v_rcp_f32_e32 v115, v115
	v_mul_f32_e32 v116, v144, v124
	v_mul_f32_e32 v117, v144, v125
	v_mul_f32_e32 v122, v144, v122
	v_mul_f32_e32 v123, v144, v123
	v_mul_f32_e32 v112, v112, v116
	v_mul_f32_e32 v113, v113, v117
	v_mul_f32_e32 v114, v144, v114
	v_mul_f32_e32 v115, v144, v115
	v_mul_f32_e32 v122, v126, v122
	v_mul_f32_e32 v123, v127, v123
	v_mul_f32_e32 v118, v118, v114
	v_mul_f32_e32 v119, v119, v115
	v_cvt_pk_bf16_f32 v114, v120, v121
	v_cvt_pk_bf16_f32 v115, v122, v123
	v_cvt_pk_bf16_f32 v116, v112, v113
	v_lshl_add_u64 v[112:113], s[46:47], 0, v[194:195]
	v_mov_b32_e32 v141, v195
	v_lshl_add_u64 v[112:113], v[112:113], 0, v[140:141]
	v_cvt_pk_bf16_f32 v117, v118, v119
	global_store_dwordx4 v[112:113], v[114:117], off nt
	s_nop 1
	v_mul_f32_e32 v114, 0xbfb8aa3b, v156
	v_mul_f32_e32 v118, v108, v114
	v_mul_f32_e32 v119, v109, v114
	v_mul_f32_e32 v116, v156, v156
	v_exp_f32_e32 v118, v118
	v_exp_f32_e32 v119, v119
	s_nop 0
	v_add_f32_e32 v118, 1.0, v118
	v_add_f32_e32 v119, 1.0, v119
	s_nop 0
	v_rcp_f32_e32 v118, v118
	v_rcp_f32_e32 v119, v119
	s_nop 0
	v_mul_f32_e32 v108, v116, v118
	v_mul_f32_e32 v109, v116, v119
	v_mul_f32_e32 v104, v104, v108
	v_mul_f32_e32 v105, v105, v109
	v_mul_f32_e32 v108, v110, v114
	v_mul_f32_e32 v109, v111, v114
	s_nop 0
	v_exp_f32_e32 v108, v108
	v_exp_f32_e32 v109, v109
	s_nop 0
	v_add_f32_e32 v108, 1.0, v108
	v_add_f32_e32 v109, 1.0, v109
	s_nop 0
	v_rcp_f32_e32 v108, v108
	v_rcp_f32_e32 v109, v109
	s_nop 0
	v_mul_f32_e32 v108, v116, v108
	v_mul_f32_e32 v109, v116, v109
	v_mul_f32_e32 v106, v106, v108
	v_mul_f32_e32 v107, v107, v109
	v_mul_f32_e32 v108, v96, v114
	v_mul_f32_e32 v109, v97, v114
	v_mul_f32_e32 v96, v96, v100
	v_mul_f32_e32 v97, v97, v101
	v_exp_f32_e32 v108, v108
	v_exp_f32_e32 v109, v109
	s_nop 0
	v_add_f32_e32 v108, 1.0, v108
	v_add_f32_e32 v109, 1.0, v109
	s_nop 0
	v_rcp_f32_e32 v108, v108
	v_rcp_f32_e32 v109, v109
	s_nop 0
	v_mul_f32_e32 v100, v116, v108
	v_mul_f32_e32 v101, v116, v109
	v_mul_f32_e32 v100, v96, v100
	v_mul_f32_e32 v101, v97, v101
	v_mul_f32_e32 v96, v98, v114
	v_mul_f32_e32 v97, v99, v114
	s_nop 0
	v_exp_f32_e32 v96, v96
	v_exp_f32_e32 v97, v97
	s_nop 0
	v_add_f32_e32 v96, 1.0, v96
	v_add_f32_e32 v97, 1.0, v97
	s_nop 0
	v_rcp_f32_e32 v96, v96
	v_rcp_f32_e32 v97, v97
	s_nop 0
	v_mul_f32_e32 v96, v116, v96
	v_mul_f32_e32 v97, v116, v97
	v_mul_f32_e32 v102, v102, v96
	v_mul_f32_e32 v103, v103, v97
	v_cvt_pk_bf16_f32 v96, v104, v105
	v_cvt_pk_bf16_f32 v97, v106, v107
	v_cvt_pk_bf16_f32 v98, v100, v101
	s_nop 0
	v_cvt_pk_bf16_f32 v99, v102, v103
	global_store_dwordx4 v[112:113], v[96:99], off offset:2048 nt
	s_nop 1
	v_mul_f32_e32 v96, 0xbfb8aa3b, v155
	v_mul_f32_e32 v100, v92, v96
	v_mul_f32_e32 v101, v93, v96
	v_mul_f32_e32 v98, v155, v155
	v_exp_f32_e32 v100, v100
	v_exp_f32_e32 v101, v101
	s_nop 0
	v_add_f32_e32 v100, 1.0, v100
	v_add_f32_e32 v101, 1.0, v101
	s_nop 0
	v_rcp_f32_e32 v100, v100
	v_rcp_f32_e32 v101, v101
	s_nop 0
	v_mul_f32_e32 v92, v98, v100
	v_mul_f32_e32 v93, v98, v101
	v_mul_f32_e32 v88, v88, v92
	v_mul_f32_e32 v89, v89, v93
	v_mul_f32_e32 v92, v94, v96
	v_mul_f32_e32 v93, v95, v96
	s_nop 0
	v_exp_f32_e32 v92, v92
	v_exp_f32_e32 v93, v93
	s_nop 0
	v_add_f32_e32 v92, 1.0, v92
	v_add_f32_e32 v93, 1.0, v93
	s_nop 0
	v_rcp_f32_e32 v92, v92
	v_rcp_f32_e32 v93, v93
	s_nop 0
	v_mul_f32_e32 v92, v98, v92
	v_mul_f32_e32 v93, v98, v93
	v_mul_f32_e32 v90, v90, v92
	v_mul_f32_e32 v91, v91, v93
	v_mul_f32_e32 v92, v80, v96
	v_mul_f32_e32 v93, v81, v96
	v_mul_f32_e32 v80, v80, v84
	v_mul_f32_e32 v81, v81, v85
	v_exp_f32_e32 v92, v92
	v_exp_f32_e32 v93, v93
	s_nop 0
	v_add_f32_e32 v92, 1.0, v92
	v_add_f32_e32 v93, 1.0, v93
	s_nop 0
	v_rcp_f32_e32 v92, v92
	v_rcp_f32_e32 v93, v93
	s_nop 0
	v_mul_f32_e32 v84, v98, v92
	v_mul_f32_e32 v85, v98, v93
	v_mul_f32_e32 v84, v80, v84
	v_mul_f32_e32 v85, v81, v85
	v_mul_f32_e32 v80, v82, v96
	v_mul_f32_e32 v81, v83, v96
	s_nop 0
	v_exp_f32_e32 v80, v80
	v_exp_f32_e32 v81, v81
	s_nop 0
	v_add_f32_e32 v80, 1.0, v80
	v_add_f32_e32 v81, 1.0, v81
	s_nop 0
	v_rcp_f32_e32 v80, v80
	v_rcp_f32_e32 v81, v81
	s_nop 0
	v_mul_f32_e32 v80, v98, v80
	v_mul_f32_e32 v81, v98, v81
	v_mul_f32_e32 v86, v86, v80
	v_mul_f32_e32 v87, v87, v81
	v_cvt_pk_bf16_f32 v80, v88, v89
	v_cvt_pk_bf16_f32 v81, v90, v91
	v_cvt_pk_bf16_f32 v82, v84, v85
	v_add_co_u32_e32 v84, vcc, s23, v112
	v_cvt_pk_bf16_f32 v83, v86, v87
	s_nop 1
	v_addc_co_u32_e32 v85, vcc, 0, v113, vcc
	global_store_dwordx4 v[84:85], v[80:83], off nt
	s_nop 1
	v_mul_f32_e32 v80, 0xbfb8aa3b, v154
	v_mul_f32_e32 v86, v76, v80
	v_mul_f32_e32 v87, v77, v80
	v_mul_f32_e32 v82, v154, v154
	v_exp_f32_e32 v86, v86
	v_exp_f32_e32 v87, v87
	s_nop 0
	v_add_f32_e32 v86, 1.0, v86
	v_add_f32_e32 v87, 1.0, v87
	s_nop 0
	v_rcp_f32_e32 v86, v86
	v_rcp_f32_e32 v87, v87
	s_nop 0
	v_mul_f32_e32 v76, v82, v86
	v_mul_f32_e32 v77, v82, v87
	v_mul_f32_e32 v72, v72, v76
	v_mul_f32_e32 v73, v73, v77
; __device__ __forceinline__ unsigned cvt_pk_bf16(float lo, float hi) { unsigned r; asm volatile("v_cvt_pk_bf16_f32 %0, %1, %2" : "=v"(r) : "v"(lo), "v"(hi)); return r; }
;     __device__ __forceinline__ void operator()(const f32x4 (&acc)[2][2][4][2], const Unit& u, int wr, int wc, int fr, int fq) const {
;     ...
;             for (int m = 0; m < 4; ++m) {
;                 const int row = row0 + ai * HALF + m * 16;
;                 const float rs = rsv[ai][m], nrs = rs * -1.44269504089f, rs2 = rs * rs;
;                 typedef float f32x2 __attribute__((ext_vector_type(2)));
;                 float a[8];
; #pragma unroll
;                 for (int n = 0; n < 2; ++n)
; #pragma unroll
;                     for (int hf = 0; hf < 2; ++hf) {
;                         const f32x2 g2 = (f32x2){acc[ai][0][m][n][2 * hf], acc[ai][0][m][n][2 * hf + 1]}, u2 = (f32x2){acc[ai][1][m][n][2 * hf], acc[ai][1][m][n][2 * hf + 1]};
;                         const f32x2 t = g2 * nrs;
;                         f32x2 e; e.x = __builtin_amdgcn_exp2f(t.x); e.y = __builtin_amdgcn_exp2f(t.y);
;                         const f32x2 d = e + 1.0f;
;                         f32x2 r; r.x = __builtin_amdgcn_rcpf(d.x); r.y = __builtin_amdgcn_rcpf(d.y);
;                         const f32x2 o = (g2 * u2) * (r * rs2);
;                         a[n * 4 + 2 * hf] = o.x; a[n * 4 + 2 * hf + 1] = o.y;
;                     }
;                 u32x4 w; w.x = cvt_pk_bf16(a[0], a[1]); w.y = cvt_pk_bf16(a[2], a[3]); w.z = cvt_pk_bf16(a[4], a[5]); w.w = cvt_pk_bf16(a[6], a[7]);
;                 __builtin_nontemporal_store(w, (u32x4*)(O + ((size_t)(u.pm * (ldc >> 6) + (col0 >> 6)) * 256 + (row & 255)) * 64 + (col0 & 63)));
	v_mul_f32_e32 v76, v78, v80
	v_mul_f32_e32 v77, v79, v80
	s_nop 0
	v_exp_f32_e32 v76, v76
	v_exp_f32_e32 v77, v77
	s_nop 0
	v_add_f32_e32 v76, 1.0, v76
	v_add_f32_e32 v77, 1.0, v77
	s_nop 0
	v_rcp_f32_e32 v76, v76
	v_rcp_f32_e32 v77, v77
	s_nop 0
	v_mul_f32_e32 v76, v82, v76
	v_mul_f32_e32 v77, v82, v77
	v_mul_f32_e32 v74, v74, v76
	v_mul_f32_e32 v75, v75, v77
	v_mul_f32_e32 v76, v64, v80
	v_mul_f32_e32 v77, v65, v80
	v_mul_f32_e32 v64, v64, v68
	v_mul_f32_e32 v65, v65, v69
	v_exp_f32_e32 v76, v76
	v_exp_f32_e32 v77, v77
	s_nop 0
	v_add_f32_e32 v76, 1.0, v76
	v_add_f32_e32 v77, 1.0, v77
	s_nop 0
	v_rcp_f32_e32 v76, v76
	v_rcp_f32_e32 v77, v77
	s_nop 0
	v_mul_f32_e32 v68, v82, v76
	v_mul_f32_e32 v69, v82, v77
	v_mul_f32_e32 v68, v64, v68
	v_mul_f32_e32 v69, v65, v69
	v_mul_f32_e32 v64, v66, v80
	v_mul_f32_e32 v65, v67, v80
	s_nop 0
	v_exp_f32_e32 v64, v64
	v_exp_f32_e32 v65, v65
	s_nop 0
	v_add_f32_e32 v64, 1.0, v64
	v_add_f32_e32 v65, 1.0, v65
	s_nop 0
	v_rcp_f32_e32 v64, v64
	v_rcp_f32_e32 v65, v65
	s_nop 0
	v_mul_f32_e32 v64, v82, v64
	v_mul_f32_e32 v65, v82, v65
	v_mul_f32_e32 v70, v70, v64
	v_mul_f32_e32 v71, v71, v65
	v_cvt_pk_bf16_f32 v64, v72, v73
	v_cvt_pk_bf16_f32 v65, v74, v75
	v_cvt_pk_bf16_f32 v66, v68, v69
	s_nop 0
	v_cvt_pk_bf16_f32 v67, v70, v71
	global_store_dwordx4 v[84:85], v[64:67], off offset:2048 nt
	s_nop 1
	v_mul_f32_e32 v64, 0xbfb8aa3b, v143
	v_mul_f32_e32 v68, v60, v64
	v_mul_f32_e32 v69, v61, v64
	v_mul_f32_e32 v66, v143, v143
	v_exp_f32_e32 v68, v68
	v_exp_f32_e32 v69, v69
	v_mul_f32_e32 v50, v50, v64
	v_mul_f32_e32 v51, v51, v64
	v_mov_b32_e32 v143, v195
	v_exp_f32_e32 v50, v50
	v_add_f32_e32 v68, 1.0, v68
	v_add_f32_e32 v69, 1.0, v69
	v_exp_f32_e32 v51, v51
	v_rcp_f32_e32 v68, v68
	v_rcp_f32_e32 v69, v69
	v_add_f32_e32 v50, 1.0, v50
	v_add_f32_e32 v51, 1.0, v51
	s_nop 0
	v_rcp_f32_e32 v50, v50
	v_mul_f32_e32 v60, v66, v68
	v_mul_f32_e32 v61, v66, v69
	v_mul_f32_e32 v56, v56, v60
	v_mul_f32_e32 v57, v57, v61
	v_mul_f32_e32 v60, v62, v64
	v_mul_f32_e32 v61, v63, v64
	v_rcp_f32_e32 v51, v51
	v_exp_f32_e32 v60, v60
	v_exp_f32_e32 v61, v61
	v_mul_f32_e32 v50, v66, v50
	v_mul_f32_e32 v51, v66, v51
	v_mul_f32_e32 v54, v54, v50
	v_mul_f32_e32 v55, v55, v51
	v_add_f32_e32 v60, 1.0, v60
	v_add_f32_e32 v61, 1.0, v61
	v_cvt_pk_bf16_f32 v50, v56, v57
	s_nop 0
	v_rcp_f32_e32 v60, v60
	v_rcp_f32_e32 v61, v61
	s_nop 0
	v_mul_f32_e32 v60, v66, v60
	v_mul_f32_e32 v61, v66, v61
	v_mul_f32_e32 v58, v58, v60
	v_mul_f32_e32 v59, v59, v61
	v_mul_f32_e32 v60, v48, v64
	v_mul_f32_e32 v61, v49, v64
	v_mul_f32_e32 v48, v48, v52
	v_mul_f32_e32 v49, v49, v53
	v_exp_f32_e32 v60, v60
	v_exp_f32_e32 v61, v61
	v_cvt_pk_bf16_f32 v51, v58, v59
	s_nop 0
	v_add_f32_e32 v60, 1.0, v60
	v_add_f32_e32 v61, 1.0, v61
	s_nop 0
	v_rcp_f32_e32 v60, v60
	v_rcp_f32_e32 v61, v61
	s_nop 0
	v_mul_f32_e32 v52, v66, v60
	v_mul_f32_e32 v53, v66, v61
	v_mul_f32_e32 v48, v48, v52
	v_mul_f32_e32 v49, v49, v53
	s_nop 0
	v_cvt_pk_bf16_f32 v52, v48, v49
	v_lshl_add_u64 v[48:49], s[46:47], 0, v[142:143]
	v_lshl_add_u64 v[48:49], v[48:49], 0, v[140:141]
	v_cvt_pk_bf16_f32 v53, v54, v55
	global_store_dwordx4 v[48:49], v[50:53], off nt
	s_mov_b64 s[46:47], -1
	s_nop 0
	v_mul_f32_e32 v50, 0xbfb8aa3b, v153
	v_mul_f32_e32 v54, v44, v50
	v_mul_f32_e32 v55, v45, v50
	v_mul_f32_e32 v52, v153, v153
	v_exp_f32_e32 v54, v54
	v_exp_f32_e32 v55, v55
	s_nop 0
	v_add_f32_e32 v54, 1.0, v54
	v_add_f32_e32 v55, 1.0, v55
	s_nop 0
	v_rcp_f32_e32 v54, v54
	v_rcp_f32_e32 v55, v55
	s_nop 0
	v_mul_f32_e32 v44, v52, v54
	v_mul_f32_e32 v45, v52, v55
	v_mul_f32_e32 v40, v40, v44
	v_mul_f32_e32 v41, v41, v45
	v_mul_f32_e32 v44, v46, v50
	v_mul_f32_e32 v45, v47, v50
	s_nop 0
	v_exp_f32_e32 v44, v44
	v_exp_f32_e32 v45, v45
	s_nop 0
	v_add_f32_e32 v44, 1.0, v44
	v_add_f32_e32 v45, 1.0, v45
	s_nop 0
	v_rcp_f32_e32 v44, v44
	v_rcp_f32_e32 v45, v45
	s_nop 0
	v_mul_f32_e32 v44, v52, v44
	v_mul_f32_e32 v45, v52, v45
	v_mul_f32_e32 v42, v42, v44
	v_mul_f32_e32 v43, v43, v45
	v_mul_f32_e32 v44, v32, v50
	v_mul_f32_e32 v45, v33, v50
	v_mul_f32_e32 v32, v32, v36
	v_mul_f32_e32 v33, v33, v37
	v_exp_f32_e32 v44, v44
	v_exp_f32_e32 v45, v45
	s_nop 0
	v_add_f32_e32 v44, 1.0, v44
	v_add_f32_e32 v45, 1.0, v45
	s_nop 0
	v_rcp_f32_e32 v44, v44
	v_rcp_f32_e32 v45, v45
	s_nop 0
	v_mul_f32_e32 v36, v52, v44
; __device__ __forceinline__ unsigned cvt_pk_bf16(float lo, float hi) { unsigned r; asm volatile("v_cvt_pk_bf16_f32 %0, %1, %2" : "=v"(r) : "v"(lo), "v"(hi)); return r; }
;     __device__ __forceinline__ void operator()(const f32x4 (&acc)[2][2][4][2], const Unit& u, int wr, int wc, int fr, int fq) const {
;     ...
;             for (int m = 0; m < 4; ++m) {
;                 const int row = row0 + ai * HALF + m * 16;
;                 const float rs = rsv[ai][m], nrs = rs * -1.44269504089f, rs2 = rs * rs;
;                 typedef float f32x2 __attribute__((ext_vector_type(2)));
;                 float a[8];
; #pragma unroll
;                 for (int n = 0; n < 2; ++n)
; #pragma unroll
;                     for (int hf = 0; hf < 2; ++hf) {
;                         const f32x2 g2 = (f32x2){acc[ai][0][m][n][2 * hf], acc[ai][0][m][n][2 * hf + 1]}, u2 = (f32x2){acc[ai][1][m][n][2 * hf], acc[ai][1][m][n][2 * hf + 1]};
;                         const f32x2 t = g2 * nrs;
;                         f32x2 e; e.x = __builtin_amdgcn_exp2f(t.x); e.y = __builtin_amdgcn_exp2f(t.y);
;                         const f32x2 d = e + 1.0f;
;                         f32x2 r; r.x = __builtin_amdgcn_rcpf(d.x); r.y = __builtin_amdgcn_rcpf(d.y);
;                         const f32x2 o = (g2 * u2) * (r * rs2);
;                         a[n * 4 + 2 * hf] = o.x; a[n * 4 + 2 * hf + 1] = o.y;
;                     }
;                 u32x4 w; w.x = cvt_pk_bf16(a[0], a[1]); w.y = cvt_pk_bf16(a[2], a[3]); w.z = cvt_pk_bf16(a[4], a[5]); w.w = cvt_pk_bf16(a[6], a[7]);
;                 __builtin_nontemporal_store(w, (u32x4*)(O + ((size_t)(u.pm * (ldc >> 6) + (col0 >> 6)) * 256 + (row & 255)) * 64 + (col0 & 63)));
;             }
;     }
	v_mul_f32_e32 v37, v52, v45
	v_mul_f32_e32 v36, v32, v36
	v_mul_f32_e32 v37, v33, v37
	v_mul_f32_e32 v32, v34, v50
	v_mul_f32_e32 v33, v35, v50
	s_nop 0
	v_exp_f32_e32 v32, v32
	v_exp_f32_e32 v33, v33
	s_nop 0
	v_add_f32_e32 v32, 1.0, v32
	v_add_f32_e32 v33, 1.0, v33
	s_nop 0
	v_rcp_f32_e32 v32, v32
	v_rcp_f32_e32 v33, v33
	s_nop 0
	v_mul_f32_e32 v32, v52, v32
	v_mul_f32_e32 v33, v52, v33
	v_mul_f32_e32 v38, v38, v32
	v_mul_f32_e32 v39, v39, v33
	v_cvt_pk_bf16_f32 v32, v40, v41
	v_cvt_pk_bf16_f32 v33, v42, v43
	v_cvt_pk_bf16_f32 v34, v36, v37
	s_nop 0
	v_cvt_pk_bf16_f32 v35, v38, v39
	global_store_dwordx4 v[48:49], v[32:35], off offset:2048 nt
	s_nop 1
	v_mul_f32_e32 v32, 0xbfb8aa3b, v152
	v_mul_f32_e32 v36, v28, v32
	v_mul_f32_e32 v37, v29, v32
	v_mul_f32_e32 v34, v152, v152
	v_exp_f32_e32 v36, v36
	v_exp_f32_e32 v37, v37
	s_nop 0
	v_add_f32_e32 v36, 1.0, v36
	v_add_f32_e32 v37, 1.0, v37
	s_nop 0
	v_rcp_f32_e32 v36, v36
	v_rcp_f32_e32 v37, v37
	s_nop 0
	v_mul_f32_e32 v28, v34, v36
	v_mul_f32_e32 v29, v34, v37
	v_mul_f32_e32 v24, v24, v28
	v_mul_f32_e32 v25, v25, v29
	v_mul_f32_e32 v28, v30, v32
	v_mul_f32_e32 v29, v31, v32
	s_nop 0
	v_exp_f32_e32 v28, v28
	v_exp_f32_e32 v29, v29
	s_nop 0
	v_add_f32_e32 v28, 1.0, v28
	v_add_f32_e32 v29, 1.0, v29
	s_nop 0
	v_rcp_f32_e32 v28, v28
	v_rcp_f32_e32 v29, v29
	s_nop 0
	v_mul_f32_e32 v28, v34, v28
	v_mul_f32_e32 v29, v34, v29
	v_mul_f32_e32 v26, v26, v28
	v_mul_f32_e32 v27, v27, v29
	v_mul_f32_e32 v28, v16, v32
	v_mul_f32_e32 v29, v17, v32
	v_mul_f32_e32 v16, v16, v20
	v_mul_f32_e32 v17, v17, v21
	v_exp_f32_e32 v28, v28
	v_exp_f32_e32 v29, v29
	s_nop 0
	v_add_f32_e32 v28, 1.0, v28
	v_add_f32_e32 v29, 1.0, v29
	s_nop 0
	v_rcp_f32_e32 v28, v28
	v_rcp_f32_e32 v29, v29
	s_nop 0
	v_mul_f32_e32 v20, v34, v28
	v_mul_f32_e32 v21, v34, v29
	v_mul_f32_e32 v20, v16, v20
	v_mul_f32_e32 v21, v17, v21
	v_mul_f32_e32 v16, v18, v32
	v_mul_f32_e32 v17, v19, v32
	s_nop 0
	v_exp_f32_e32 v16, v16
	v_exp_f32_e32 v17, v17
	s_nop 0
	v_add_f32_e32 v16, 1.0, v16
	v_add_f32_e32 v17, 1.0, v17
	s_nop 0
	v_rcp_f32_e32 v16, v16
	v_rcp_f32_e32 v17, v17
	s_nop 0
	v_mul_f32_e32 v16, v34, v16
	v_mul_f32_e32 v17, v34, v17
	v_mul_f32_e32 v22, v22, v16
	v_mul_f32_e32 v23, v23, v17
	v_cvt_pk_bf16_f32 v16, v24, v25
	v_cvt_pk_bf16_f32 v17, v26, v27
	v_cvt_pk_bf16_f32 v18, v20, v21
	v_add_co_u32_e32 v20, vcc, s23, v48
	v_cvt_pk_bf16_f32 v19, v22, v23
	s_nop 1
	v_addc_co_u32_e32 v21, vcc, 0, v49, vcc
	global_store_dwordx4 v[20:21], v[16:19], off nt
	s_andn2_b64 vcc, exec, s[36:37]
	s_nop 0
	v_mul_f32_e32 v16, 0xbfb8aa3b, v151
	v_mul_f32_e32 v22, v12, v16
	v_mul_f32_e32 v23, v13, v16
	v_mul_f32_e32 v18, v151, v151
	v_exp_f32_e32 v22, v22
	v_exp_f32_e32 v23, v23
	s_nop 0
	v_add_f32_e32 v22, 1.0, v22
	v_add_f32_e32 v23, 1.0, v23
	s_nop 0
	v_rcp_f32_e32 v22, v22
	v_rcp_f32_e32 v23, v23
	s_nop 0
	v_mul_f32_e32 v12, v18, v22
	v_mul_f32_e32 v13, v18, v23
	v_mul_f32_e32 v8, v8, v12
	v_mul_f32_e32 v9, v9, v13
	v_mul_f32_e32 v12, v14, v16
	v_mul_f32_e32 v13, v15, v16
	s_nop 0
	v_exp_f32_e32 v12, v12
	v_exp_f32_e32 v13, v13
	s_nop 0
	v_add_f32_e32 v12, 1.0, v12
	v_add_f32_e32 v13, 1.0, v13
	s_nop 0
	v_rcp_f32_e32 v12, v12
	v_rcp_f32_e32 v13, v13
	s_nop 0
	v_mul_f32_e32 v12, v18, v12
	v_mul_f32_e32 v13, v18, v13
	v_mul_f32_e32 v10, v10, v12
	v_mul_f32_e32 v11, v11, v13
	v_mul_f32_e32 v12, v4, v16
	v_mul_f32_e32 v13, v5, v16
	s_nop 0
	v_exp_f32_e32 v12, v12
	v_exp_f32_e32 v13, v13
	s_nop 0
	v_add_f32_e32 v12, 1.0, v12
	v_add_f32_e32 v13, 1.0, v13
	s_nop 0
	v_rcp_f32_e32 v12, v12
	v_rcp_f32_e32 v13, v13
	s_nop 0
	v_mul_f32_e32 v4, v18, v12
	v_mul_f32_e32 v5, v18, v13
	v_mul_f32_e32 v4, v0, v4
	v_mul_f32_e32 v5, v1, v5
	v_mul_f32_e32 v0, v6, v16
	v_mul_f32_e32 v1, v7, v16
	s_nop 0
	v_exp_f32_e32 v0, v0
	v_exp_f32_e32 v1, v1
	s_nop 0
	v_add_f32_e32 v0, 1.0, v0
	v_add_f32_e32 v1, 1.0, v1
	s_nop 0
	v_rcp_f32_e32 v0, v0
	v_rcp_f32_e32 v1, v1
	s_nop 0
	v_mul_f32_e32 v0, v18, v0
	v_mul_f32_e32 v1, v18, v1
	v_mul_f32_e32 v6, v2, v0
	v_mul_f32_e32 v7, v3, v1
	v_cvt_pk_bf16_f32 v0, v8, v9
	v_cvt_pk_bf16_f32 v1, v10, v11
	v_cvt_pk_bf16_f32 v2, v4, v5
	s_nop 0
	v_cvt_pk_bf16_f32 v3, v6, v7
	global_store_dwordx4 v[20:21], v[0:3], off offset:2048 nt
	s_cbranch_vccnz .LBB0_124
	s_andn2_b64 vcc, exec, s[0:1]
	s_cbranch_vccnz .LBB0_123
	s_barrier
	s_branch .LBB0_123
